# S5 set-up item at kernel start: Kt stage rewritten (one packed FMA per column and p, C-table rows XOR-swizzled against an 8-way LDS bank conflict)
# speedup vs baseline: 1.0044x; 1.0044x over previous
.Lssa_469:
	global_load_dword v56, v[6:7], off
	global_load_dword v54, v[48:49], off
	v_and_b32_e32 v50, 0xfc, v8
	v_lshl_or_b32 v51, v8, 3, 24
	v_lshl_add_u32 v50, v50, 3, 0
	v_add_u32_e32 v52, 0, v51
	ds_read_b64 v[50:51], v50 offset:25104
	ds_read_b64 v[52:53], v52 offset:25088
	v_add_co_u32_e32 v44, vcc, 0x200, v44
	s_xor_b64 s[84:85], vcc, -1
	s_and_b64 s[84:85], exec, s[84:85]
	v_lshl_add_u64 v[6:7], v[6:7], 0, s[80:81]
	v_lshl_add_u64 v[48:49], v[48:49], 0, s[80:81]
	v_add_u32_e32 v8, 0x80, v8
	s_or_b64 s[4:5], s[84:85], s[4:5]
	s_waitcnt vmcnt(1)
	v_cvt_f64_f32_e32 v[56:57], v56
	s_waitcnt vmcnt(0)
	v_cvt_f64_f32_e32 v[54:55], v54
	s_waitcnt lgkmcnt(0)
	v_mul_f64 v[58:59], v[52:53], v[56:57]
	v_mul_f64 v[56:57], v[50:51], v[56:57]
	v_fma_f64 v[50:51], v[50:51], v[54:55], -v[58:59]
	v_fmac_f64_e32 v[56:57], v[52:53], v[54:55]
	v_cvt_f32_f64_e32 v50, v[50:51]
	v_cvt_f32_f64_e32 v51, v[56:57]
	ds_write_b64 v37, v[50:51]
	v_add_u32_e32 v37, 0x1000, v37
	s_andn2_b64 exec, exec, s[4:5]
	s_cbranch_execnz .Lssa_469
	s_or_b64 exec, exec, s[4:5]
	v_lshl_add_u64 v[6:7], s[18:19], 0, v[4:5]
	v_lshl_add_u64 v[4:5], s[16:17], 0, v[4:5]
	s_mov_b64 s[4:5], 0
	v_mov_b32_e32 v8, v75
	v_lshrrev_b32_e32 v116, 6, v208
	v_and_b32_e32 v116, 7, v116
	v_lshlrev_b32_e32 v116, 4, v116
	v_xor_b32_e32 v8, v116, v8
	v_mov_b32_e32 v37, v72
.Lssa_471:
	global_load_dword v48, v[4:5], off
	global_load_dword v49, v[6:7], off
	v_add_co_u32_e32 v37, vcc, 0x200, v37
	s_xor_b64 s[84:85], vcc, -1
	s_and_b64 s[84:85], exec, s[84:85]
	v_lshl_add_u64 v[6:7], v[6:7], 0, s[80:81]
	v_lshl_add_u64 v[4:5], v[4:5], 0, s[80:81]
	s_or_b64 s[4:5], s[84:85], s[4:5]
	s_waitcnt vmcnt(0)
	ds_write_b64 v8, v[48:49]
	v_add_u32_e32 v8, 0x1000, v8
	s_andn2_b64 exec, exec, s[4:5]
	s_cbranch_execnz .Lssa_471
	s_or_b64 exec, exec, s[4:5]
	v_mov_b32_e32 v4, 0
	s_mov_b32 s4, 0
	v_mov_b32_e32 v8, v77
	v_mov_b32_e32 v5, v4
	v_mov_b32_e32 v50, v4
	v_mov_b32_e32 v51, v4
	v_mov_b32_e32 v48, v4
	v_mov_b32_e32 v49, v4
	v_mov_b32_e32 v6, v4
	v_mov_b32_e32 v7, v4
	v_mov_b32_e32 v112, v4
	v_mov_b32_e32 v113, v4
	v_mov_b32_e32 v114, v4
	v_mov_b32_e32 v115, v4
	v_mov_b32_e32 v116, v4
	v_mov_b32_e32 v117, v4
	v_mov_b32_e32 v118, v4
	v_mov_b32_e32 v119, v4
	v_and_b32_e32 v12, 14, v208
	v_lshlrev_b32_e32 v12, 3, v12
	s_waitcnt lgkmcnt(0)
	s_barrier
.Lssa_473:
	v_add_u32_e32 v44, s4, v67
	v_add_u32_e32 v37, s4, v76
	v_xor_b32_e32 v37, v12, v37
	ds_read_b128 v[102:105], v44
	ds_read_b128 v[106:109], v37
	ds_read_b128 v[52:55], v8
	ds_read_b128 v[56:59], v8 offset:16
	ds_read_b128 v[60:63], v8 offset:32
	ds_read_b128 v[82:85], v8 offset:48
	ds_read_b128 v[86:89], v8 offset:128
	ds_read_b128 v[90:93], v8 offset:144
	ds_read_b128 v[94:97], v8 offset:160
	ds_read_b128 v[98:101], v8 offset:176
	s_waitcnt lgkmcnt(8)
	v_pk_mul_f32 v[110:111], v[106:107], v[102:103] op_sel:[1,1] op_sel_hi:[0,1]
	v_pk_fma_f32 v[110:111], v[106:107], v[102:103], v[110:111] op_sel_hi:[1,0,1] neg_lo:[0,0,1]
	s_waitcnt lgkmcnt(7)
	v_pk_fma_f32 v[112:113], v[110:111], v[52:53], v[112:113]
	v_pk_fma_f32 v[114:115], v[110:111], v[54:55], v[114:115]
	s_waitcnt lgkmcnt(6)
	v_pk_fma_f32 v[116:117], v[110:111], v[56:57], v[116:117]
	v_pk_fma_f32 v[118:119], v[110:111], v[58:59], v[118:119]
	s_waitcnt lgkmcnt(5)
	v_pk_fma_f32 v[48:49], v[110:111], v[60:61], v[48:49]
	v_pk_fma_f32 v[50:51], v[110:111], v[62:63], v[50:51]
	s_waitcnt lgkmcnt(4)
	v_pk_fma_f32 v[4:5], v[110:111], v[82:83], v[4:5]
	v_pk_fma_f32 v[6:7], v[110:111], v[84:85], v[6:7]
	v_pk_mul_f32 v[110:111], v[108:109], v[104:105] op_sel:[1,1] op_sel_hi:[0,1]
	v_pk_fma_f32 v[110:111], v[108:109], v[104:105], v[110:111] op_sel_hi:[1,0,1] neg_lo:[0,0,1]
	s_waitcnt lgkmcnt(3)
	v_pk_fma_f32 v[112:113], v[110:111], v[86:87], v[112:113]
	v_pk_fma_f32 v[114:115], v[110:111], v[88:89], v[114:115]
	s_waitcnt lgkmcnt(2)
	v_pk_fma_f32 v[116:117], v[110:111], v[90:91], v[116:117]
	v_pk_fma_f32 v[118:119], v[110:111], v[92:93], v[118:119]
	s_waitcnt lgkmcnt(1)
	v_pk_fma_f32 v[48:49], v[110:111], v[94:95], v[48:49]
	v_pk_fma_f32 v[50:51], v[110:111], v[96:97], v[50:51]
	s_waitcnt lgkmcnt(0)
	v_pk_fma_f32 v[4:5], v[110:111], v[98:99], v[4:5]
	v_pk_fma_f32 v[6:7], v[110:111], v[100:101], v[6:7]
	s_add_i32 s4, s4, 16
	v_add_u32_e32 v8, 0x100, v8
	s_cmpk_eq_i32 s4, 0x200
	s_cbranch_scc0 .Lssa_473
	v_sub_f32_e32 v52, v112, v113
	v_sub_f32_e32 v53, v114, v115
	v_sub_f32_e32 v54, v116, v117
	v_sub_f32_e32 v55, v118, v119
	v_sub_f32_e32 v56, v48, v49
	v_sub_f32_e32 v57, v50, v51
	v_sub_f32_e32 v58, v4, v5
	v_sub_f32_e32 v59, v6, v7
	v_mov_b32_e32 v50, v52
	v_mov_b32_e32 v51, v53
	v_mov_b32_e32 v48, v54
	v_mov_b32_e32 v49, v55
	v_mov_b32_e32 v6, v56
	v_mov_b32_e32 v7, v57
	v_mov_b32_e32 v4, v58
	v_mov_b32_e32 v5, v59
	v_lshl_add_u32 v52, s82, 4, v66
	v_ashrrev_i32_e32 v53, 31, v52
	v_mov_b32_e32 v8, 0
	v_mov_b32_e32 v37, 0
	s_and_saveexec_b64 s[4:5], s[42:43]
	s_cbranch_execz .Lssa_476
	s_load_dwordx2 s[84:85], s[22:23], 0x80
	s_waitcnt lgkmcnt(0)
	v_lshl_add_u64 v[54:55], v[52:53], 2, s[84:85]
	global_load_dword v37, v[54:55], off

.Lssa_493:
	v_add_u32_e32 v4, s91, v208
	v_mul_hi_u32 v6, v4, s95
	v_lshrrev_b32_e32 v5, 5, v6
	v_mul_lo_u32 v7, v5, 48
	v_sub_u32_e32 v51, v4, v7
	v_add_u32_e32 v5, s86, v5
	v_lshlrev_b32_e32 v4, 3, v51
	v_lshrrev_b32_e32 v52, 4, v5
	v_bfe_u32 v53, v6, 5, 4
	v_and_b32_e32 v13, 7, v53
	v_lshlrev_b32_e32 v13, 4, v13
	v_cmp_lt_u32_e32 vcc, 31, v51
	s_and_saveexec_b64 s[4:5], vcc
	s_xor_b64 s[4:5], exec, s[4:5]
	s_cbranch_execz .Lssa_495
	v_and_b32_e32 v44, 56, v4
	v_lshl_add_u32 v62, v53, 9, 0
	v_lshl_add_u32 v63, v52, 6, 64
	v_lshl_add_u32 v6, v44, 3, v62
	v_xor_b32_e32 v6, v13, v6
	ds_read_b128 v[52:55], v6 offset:16896
	v_or_b32_e32 v6, v63, v44
	v_lshl_add_u32 v6, v6, 3, 0
	ds_read_b128 v[56:59], v6
	v_and_b32_e32 v8, 56, v51
	s_waitcnt lgkmcnt(1)
	v_mov_b32_e32 v6, v53
	v_mov_b32_e32 v7, v54
	v_cmp_eq_u32_e32 vcc, 32, v8
	s_waitcnt lgkmcnt(0)
	v_mov_b32_e32 v50, v56
	v_mov_b32_e32 v51, v59
	v_mov_b32_e32 v48, v57
	v_mov_b32_e32 v49, v58
	v_pk_mul_f32 v[6:7], v[6:7], v[50:51]
	v_mov_b32_e32 v50, v52
	v_mov_b32_e32 v51, v55
	v_pk_fma_f32 v[60:61], v[50:51], v[48:49], v[6:7]
	v_mov_b32_e32 v7, v54
	v_mov_b32_e32 v54, v53
	v_mov_b32_e32 v58, v57
	v_mov_b32_e32 v6, v52
	v_mov_b32_e32 v48, v56
	v_pk_mul_f32 v[50:51], v[54:55], v[58:59]
	v_or_b32_e32 v8, 4, v44
	v_pk_fma_f32 v[56:57], v[6:7], v[48:49], v[50:51] neg_lo:[0,0,1] neg_hi:[0,0,1]
	v_or_b32_e32 v6, 2, v44
	v_lshl_add_u32 v7, v6, 3, v62
	v_xor_b32_e32 v7, v13, v7
	v_or_b32_e32 v6, v63, v6
	v_lshl_add_u32 v6, v6, 3, 0
	ds_read_b128 v[48:51], v7 offset:16896
	ds_read_b128 v[52:55], v6
	v_cndmask_b32_e64 v7, -v60, v56, vcc
	v_cndmask_b32_e64 v6, -v61, v57, vcc
	v_lshl_add_u32 v37, v8, 3, v62
	v_xor_b32_e32 v37, v13, v37
	s_waitcnt lgkmcnt(1)
	v_mov_b32_e32 v56, v49
	v_mov_b32_e32 v57, v50
	s_waitcnt lgkmcnt(0)
	v_mov_b32_e32 v60, v52
	v_mov_b32_e32 v61, v55
	v_mov_b32_e32 v58, v53
	v_mov_b32_e32 v59, v54
	v_pk_mul_f32 v[56:57], v[56:57], v[60:61]
	v_mov_b32_e32 v60, v48
	v_mov_b32_e32 v61, v51
	v_pk_fma_f32 v[56:57], v[60:61], v[58:59], v[56:57]
	v_mov_b32_e32 v59, v50
	v_mov_b32_e32 v61, v54
	v_mov_b32_e32 v50, v49
	v_mov_b32_e32 v54, v53
	v_or_b32_e32 v8, v63, v8
	v_mov_b32_e32 v58, v48
	v_mov_b32_e32 v60, v52
	v_pk_mul_f32 v[48:49], v[50:51], v[54:55]
	v_lshl_add_u32 v8, v8, 3, 0
	v_pk_fma_f32 v[58:59], v[58:59], v[60:61], v[48:49] neg_lo:[0,0,1] neg_hi:[0,0,1]
	ds_read_b128 v[48:51], v37 offset:16896
	ds_read_b128 v[52:55], v8
	v_cndmask_b32_e64 v37, -v56, v58, vcc
	v_cndmask_b32_e64 v8, -v57, v59, vcc
	v_or_b32_e32 v44, 6, v44
	s_waitcnt lgkmcnt(1)
	v_mov_b32_e32 v56, v49
	v_mov_b32_e32 v57, v50
	s_waitcnt lgkmcnt(0)
	v_mov_b32_e32 v60, v52
	v_mov_b32_e32 v61, v55
	v_mov_b32_e32 v58, v53
	v_mov_b32_e32 v59, v54
	v_pk_mul_f32 v[56:57], v[56:57], v[60:61]
	v_mov_b32_e32 v60, v48
	v_mov_b32_e32 v61, v51
	v_mov_b32_e32 v84, v48
	v_lshl_add_u32 v48, v44, 3, v62
	v_xor_b32_e32 v48, v13, v48
	v_or_b32_e32 v44, v63, v44
	v_pk_fma_f32 v[82:83], v[60:61], v[58:59], v[56:57]
	v_lshl_add_u32 v44, v44, 3, 0
	ds_read_b128 v[56:59], v48 offset:16896
	ds_read_b128 v[60:63], v44
	v_mov_b32_e32 v85, v50
	v_mov_b32_e32 v87, v54
	v_mov_b32_e32 v50, v49
	v_mov_b32_e32 v54, v53
	v_mov_b32_e32 v86, v52
	v_pk_mul_f32 v[48:49], v[50:51], v[54:55]
	s_waitcnt lgkmcnt(0)
	v_pk_mul_f32 v[50:51], v[56:57], v[60:61] op_sel:[1,0] op_sel_hi:[0,1]
	v_pk_fma_f32 v[48:49], v[84:85], v[86:87], v[48:49] neg_lo:[0,0,1] neg_hi:[0,0,1]
	s_nop 0
	v_cndmask_b32_e64 v44, -v83, v49, vcc
	v_add_f32_e32 v49, v50, v51
	v_pk_mul_f32 v[50:51], v[56:57], v[60:61]
	v_cndmask_b32_e64 v48, -v82, v48, vcc
	v_sub_f32_e32 v50, v50, v51
	v_cndmask_b32_e64 v49, -v49, v50, vcc
	v_pk_mul_f32 v[50:51], v[58:59], v[62:63] op_sel:[1,0] op_sel_hi:[0,1]
	v_add_f32_e32 v52, v50, v51
	v_pk_mul_f32 v[50:51], v[58:59], v[62:63]
	s_nop 0
	v_sub_f32_e32 v50, v50, v51
	v_cndmask_b32_e64 v50, -v52, v50, vcc
